# all latency edits combined: epilogue scalar-load hoists (P7,P2,P9), P9 deferred atomics, fast kmean, P0 rope 2-load merge + p-convert unroll
# speedup vs baseline: 1.0127x; 1.0023x over previous
.LBB0_86:
	s_mov_b32 s0, 0x100000
	v_cmp_gt_i32_e32 vcc, s0, v134
	s_and_saveexec_b64 s[0:1], vcc
	s_cbranch_execz .LBB0_89
	v_ashrrev_i32_e32 v135, 31, v134
	v_mov_b32_e32 v2, s54
	v_mov_b32_e32 v3, s55
	s_ashr_i32 s75, s74, 31
	v_lshl_add_u64 v[4:5], v[134:135], 3, s[8:9]
	s_mov_b64 s[10:11], 0x6c00000
	v_lshl_add_u64 v[2:3], v[134:135], 4, v[2:3]
	s_lshl_b64 s[6:7], s[74:75], 4
	v_lshl_add_u64 v[4:5], v[4:5], 0, s[10:11]
	s_lshl_b64 s[10:11], s[74:75], 3
	s_mov_b64 s[12:13], 0
	s_movk_i32 s14, 0x7fff
	s_mov_b32 s15, 0xffff0000
	s_mov_b32 s16, 0xfffff
	v_mov_b32_e32 v6, v134
	s_cmp_lg_u32 s74, 0x20000
	s_cbranch_scc1 .LBB0_88
	global_load_dwordx4 v[140:143], v[2:3], off
	v_lshl_add_u64 v[2:3], v[2:3], 0, s[6:7]
	global_load_dwordx4 v[144:147], v[2:3], off
	v_lshl_add_u64 v[2:3], v[2:3], 0, s[6:7]
	global_load_dwordx4 v[148:151], v[2:3], off
	v_lshl_add_u64 v[2:3], v[2:3], 0, s[6:7]
	global_load_dwordx4 v[152:155], v[2:3], off
	v_lshl_add_u64 v[2:3], v[2:3], 0, s[6:7]
	global_load_dwordx4 v[156:159], v[2:3], off
	v_lshl_add_u64 v[2:3], v[2:3], 0, s[6:7]
	global_load_dwordx4 v[160:163], v[2:3], off
	v_lshl_add_u64 v[2:3], v[2:3], 0, s[6:7]
	global_load_dwordx4 v[164:167], v[2:3], off
	v_lshl_add_u64 v[2:3], v[2:3], 0, s[6:7]
	global_load_dwordx4 v[168:171], v[2:3], off
	s_waitcnt vmcnt(7)
	v_bfe_u32 v7, v140, 16, 1
	v_bfe_u32 v12, v141, 16, 1
	v_bfe_u32 v13, v142, 16, 1
	v_bfe_u32 v14, v143, 16, 1
	v_add3_u32 v7, v140, v7, s14
	v_add3_u32 v8, v141, v12, s14
	v_add3_u32 v9, v142, v13, s14
	v_add3_u32 v10, v143, v14, s14
	v_lshrrev_b32_e32 v7, 16, v7
	v_lshrrev_b32_e32 v9, 16, v9
	v_and_or_b32 v8, v8, s15, v7
	v_and_or_b32 v9, v10, s15, v9
	global_store_dwordx2 v[4:5], v[8:9], off
	v_lshl_add_u64 v[4:5], v[4:5], 0, s[10:11]
	s_waitcnt vmcnt(7)
	v_bfe_u32 v7, v144, 16, 1
	v_bfe_u32 v12, v145, 16, 1
	v_bfe_u32 v13, v146, 16, 1
	v_bfe_u32 v14, v147, 16, 1
	v_add3_u32 v7, v144, v7, s14
	v_add3_u32 v8, v145, v12, s14
	v_add3_u32 v9, v146, v13, s14
	v_add3_u32 v10, v147, v14, s14
	v_lshrrev_b32_e32 v7, 16, v7
	v_lshrrev_b32_e32 v9, 16, v9
	v_and_or_b32 v8, v8, s15, v7
	v_and_or_b32 v9, v10, s15, v9
	global_store_dwordx2 v[4:5], v[8:9], off
	v_lshl_add_u64 v[4:5], v[4:5], 0, s[10:11]
	s_waitcnt vmcnt(7)
	v_bfe_u32 v7, v148, 16, 1
	v_bfe_u32 v12, v149, 16, 1
	v_bfe_u32 v13, v150, 16, 1
	v_bfe_u32 v14, v151, 16, 1
	v_add3_u32 v7, v148, v7, s14
	v_add3_u32 v8, v149, v12, s14
	v_add3_u32 v9, v150, v13, s14
	v_add3_u32 v10, v151, v14, s14
	v_lshrrev_b32_e32 v7, 16, v7
	v_lshrrev_b32_e32 v9, 16, v9
	v_and_or_b32 v8, v8, s15, v7
	v_and_or_b32 v9, v10, s15, v9
	global_store_dwordx2 v[4:5], v[8:9], off
	v_lshl_add_u64 v[4:5], v[4:5], 0, s[10:11]
	s_waitcnt vmcnt(7)
	v_bfe_u32 v7, v152, 16, 1
	v_bfe_u32 v12, v153, 16, 1
	v_bfe_u32 v13, v154, 16, 1
	v_bfe_u32 v14, v155, 16, 1
	v_add3_u32 v7, v152, v7, s14
	v_add3_u32 v8, v153, v12, s14
	v_add3_u32 v9, v154, v13, s14
	v_add3_u32 v10, v155, v14, s14
	v_lshrrev_b32_e32 v7, 16, v7
	v_lshrrev_b32_e32 v9, 16, v9
	v_and_or_b32 v8, v8, s15, v7
	v_and_or_b32 v9, v10, s15, v9
	global_store_dwordx2 v[4:5], v[8:9], off
	v_lshl_add_u64 v[4:5], v[4:5], 0, s[10:11]
	s_waitcnt vmcnt(7)
	v_bfe_u32 v7, v156, 16, 1
	v_bfe_u32 v12, v157, 16, 1
	v_bfe_u32 v13, v158, 16, 1
	v_bfe_u32 v14, v159, 16, 1
	v_add3_u32 v7, v156, v7, s14
	v_add3_u32 v8, v157, v12, s14
	v_add3_u32 v9, v158, v13, s14
	v_add3_u32 v10, v159, v14, s14
	v_lshrrev_b32_e32 v7, 16, v7
	v_lshrrev_b32_e32 v9, 16, v9
	v_and_or_b32 v8, v8, s15, v7
	v_and_or_b32 v9, v10, s15, v9
	global_store_dwordx2 v[4:5], v[8:9], off
	v_lshl_add_u64 v[4:5], v[4:5], 0, s[10:11]
	s_waitcnt vmcnt(7)
	v_bfe_u32 v7, v160, 16, 1
	v_bfe_u32 v12, v161, 16, 1
	v_bfe_u32 v13, v162, 16, 1
	v_bfe_u32 v14, v163, 16, 1
	v_add3_u32 v7, v160, v7, s14
	v_add3_u32 v8, v161, v12, s14
	v_add3_u32 v9, v162, v13, s14
	v_add3_u32 v10, v163, v14, s14
	v_lshrrev_b32_e32 v7, 16, v7
	v_lshrrev_b32_e32 v9, 16, v9
	v_and_or_b32 v8, v8, s15, v7
	v_and_or_b32 v9, v10, s15, v9
	global_store_dwordx2 v[4:5], v[8:9], off
	v_lshl_add_u64 v[4:5], v[4:5], 0, s[10:11]
	s_waitcnt vmcnt(7)
	v_bfe_u32 v7, v164, 16, 1
	v_bfe_u32 v12, v165, 16, 1
	v_bfe_u32 v13, v166, 16, 1
	v_bfe_u32 v14, v167, 16, 1
	v_add3_u32 v7, v164, v7, s14
	v_add3_u32 v8, v165, v12, s14
	v_add3_u32 v9, v166, v13, s14
	v_add3_u32 v10, v167, v14, s14
	v_lshrrev_b32_e32 v7, 16, v7
	v_lshrrev_b32_e32 v9, 16, v9
	v_and_or_b32 v8, v8, s15, v7
	v_and_or_b32 v9, v10, s15, v9
	global_store_dwordx2 v[4:5], v[8:9], off
	v_lshl_add_u64 v[4:5], v[4:5], 0, s[10:11]
	s_waitcnt vmcnt(7)
	v_bfe_u32 v7, v168, 16, 1
	v_bfe_u32 v12, v169, 16, 1
	v_bfe_u32 v13, v170, 16, 1
	v_bfe_u32 v14, v171, 16, 1
	v_add3_u32 v7, v168, v7, s14
	v_add3_u32 v8, v169, v12, s14
	v_add3_u32 v9, v170, v13, s14
	v_add3_u32 v10, v171, v14, s14
	v_lshrrev_b32_e32 v7, 16, v7
	v_lshrrev_b32_e32 v9, 16, v9
	v_and_or_b32 v8, v8, s15, v7
	v_and_or_b32 v9, v10, s15, v9
	global_store_dwordx2 v[4:5], v[8:9], off
	s_branch .LBB0_89

.LBB0_91:
	s_or_b64 exec, exec, s[82:83]
	global_load_dword v2, v[12:13], off
	s_waitcnt vmcnt(1)
	v_cvt_f32_i32_e32 v5, v5
	v_lshl_add_u64 v[12:13], s[8:9], 0, v[14:15]
	v_lshlrev_b64 v[6:7], v10, v[6:7]
	v_lshl_add_u64 v[6:7], v[12:13], 0, v[6:7]
	v_lshl_add_u64 v[6:7], v[8:9], 3, v[6:7]
	s_mov_b32 s80, s78
	v_add_u32_e32 v4, s74, v4
	v_cmp_lt_i32_e32 vcc, s35, v4
	s_or_b64 s[6:7], vcc, s[6:7]
	s_waitcnt vmcnt(0)
	v_mul_f32_e32 v2, v2, v5
	v_cvt_f64_f32_e32 v[8:9], v2
	v_mul_f64 v[10:11], v[8:9], s[10:11]
	v_rndne_f64_e32 v[10:11], v[10:11]
	v_fma_f64 v[8:9], v[8:9], s[10:11], -v[10:11]
	v_mul_f64 v[8:9], v[8:9], s[12:13]
	v_mul_f64 v[10:11], v[8:9], v[8:9]
	v_fma_f64 v[12:13], v[10:11], s[14:15], 1.0
	v_fma_f64 v[14:15], v[10:11], s[16:17], 1.0
	v_mul_f64 v[12:13], v[10:11], v[12:13]
	v_mul_f64 v[14:15], v[10:11], v[14:15]
	v_fma_f64 v[12:13], v[12:13], s[18:19], 1.0
	v_fma_f64 v[14:15], v[14:15], s[20:21], 1.0
	v_mul_f64 v[12:13], v[10:11], v[12:13]
	v_mul_f64 v[14:15], v[10:11], v[14:15]
	v_fma_f64 v[12:13], v[12:13], s[22:23], 1.0
	v_fma_f64 v[14:15], v[14:15], s[24:25], 1.0
	v_mul_f64 v[12:13], v[10:11], v[12:13]
	v_mul_f64 v[14:15], v[10:11], v[14:15]
	v_fma_f64 v[12:13], v[12:13], s[36:37], 1.0
	v_fma_f64 v[14:15], v[14:15], s[38:39], 1.0
	v_mul_f64 v[12:13], v[10:11], v[12:13]
	v_mul_f64 v[14:15], v[10:11], v[14:15]
	v_fma_f64 v[12:13], v[12:13], s[40:41], 1.0
	v_fma_f64 v[14:15], v[14:15], s[42:43], 1.0
	v_mul_f64 v[12:13], v[10:11], v[12:13]
	v_mul_f64 v[14:15], v[10:11], v[14:15]
	v_fma_f64 v[12:13], v[12:13], s[44:45], 1.0
	v_fma_f64 v[14:15], v[14:15], s[46:47], 1.0
	v_mul_f64 v[12:13], v[10:11], v[12:13]
	v_mul_f64 v[14:15], v[10:11], v[14:15]
	v_fma_f64 v[12:13], v[12:13], s[50:51], 1.0
	v_fma_f64 v[14:15], v[14:15], s[54:55], 1.0
	v_mul_f64 v[12:13], v[10:11], v[12:13]
	v_mul_f64 v[14:15], v[10:11], v[14:15]
	v_fma_f64 v[12:13], v[12:13], s[58:59], 1.0
	v_fma_f64 v[14:15], v[14:15], s[60:61], 1.0
	v_mul_f64 v[12:13], v[10:11], v[12:13]
	v_mul_f64 v[14:15], v[10:11], v[14:15]
	v_fma_f64 v[12:13], v[12:13], s[62:63], 1.0
	v_fma_f64 v[14:15], v[14:15], s[64:65], 1.0
	v_mul_f64 v[12:13], v[10:11], v[12:13]
	v_mul_f64 v[14:15], v[10:11], v[14:15]
	v_fma_f64 v[12:13], v[12:13], s[66:67], 1.0
	v_fma_f64 v[14:15], v[14:15], s[70:71], 1.0
	v_mul_f64 v[12:13], v[10:11], v[12:13]
	v_mul_f64 v[14:15], v[10:11], v[14:15]
	v_fma_f64 v[12:13], v[12:13], s[72:73], 1.0
	v_fma_f64 v[14:15], v[14:15], s[48:49], 1.0
	v_mul_f64 v[12:13], v[10:11], v[12:13]
	v_mul_f64 v[14:15], v[10:11], v[14:15]
	v_fma_f64 v[12:13], v[12:13], s[76:77], 1.0
	v_fma_f64 v[14:15], v[14:15], s[78:79], 1.0
	v_mul_f64 v[12:13], v[10:11], v[12:13]
	v_mul_f64 v[10:11], v[10:11], v[14:15]
	v_fma_f64 v[12:13], v[12:13], s[80:81], 1.0
	v_fma_f64 v[10:11], v[10:11], -0.5, 1.0
	v_mul_f64 v[8:9], v[8:9], v[12:13]
	v_cvt_f32_f64_e32 v10, v[10:11]
	v_cvt_f32_f64_e32 v11, v[8:9]
	flat_store_dwordx2 v[6:7], v[10:11]
	s_andn2_b64 exec, exec, s[6:7]
	s_cbranch_execz .LBB0_96
.LBB0_92:
	v_mul_hi_i32 v2, v4, s27
	v_lshrrev_b32_e32 v5, 31, v2
	v_ashrrev_i32_e32 v2, 4, v2
	v_add_u32_e32 v6, v2, v5
	v_ashrrev_i32_e32 v7, 31, v6
	v_lshl_add_u64 v[8:9], v[6:7], 2, s[56:57]
	global_load_dword v5, v[8:9], off
	v_mul_lo_u32 v8, v6, s33
	v_add_u32_e32 v8, v8, v4
	v_cmp_lt_i32_e32 vcc, 63, v8
	s_and_saveexec_b64 s[82:83], vcc
	s_xor_b64 s[82:83], exec, s[82:83]
	v_subrev_u32_e32 v2, 64, v8
	s_getpc_b64 s[84:85]
	s_add_u32 s84, s84, _ZL5INV64@rel32@lo+4
	s_addc_u32 s85, s85, _ZL5INV64@rel32@hi+12
	v_lshl_add_u64 v[12:13], v[2:3], 2, s[84:85]
	v_mov_b64_e32 v[8:9], v[2:3]
	s_or_saveexec_b64 s[82:83], s[82:83]
	v_mov_b64_e32 v[14:15], 0x7c00000
	v_mov_b64_e32 v[10:11], 8
	s_xor_b64 exec, exec, s[82:83]
	s_cbranch_execz .LBB0_91
	v_ashrrev_i32_e32 v9, 31, v8
	s_getpc_b64 s[84:85]
	s_add_u32 s84, s84, _ZL6INV128@rel32@lo+4
	s_addc_u32 s85, s85, _ZL6INV128@rel32@hi+12
	v_lshl_add_u64 v[12:13], v[8:9], 2, s[84:85]
	v_mov_b64_e32 v[14:15], 0x7400000
	v_mov_b64_e32 v[10:11], 9
	s_branch .LBB0_91
